# P2c tail: gnorm loads issued together, stores deferred
# speedup vs baseline: 1.0040x; 1.0040x over previous
; __device__ __forceinline__ unsigned pk2(float lo, float hi) { return cvtpk_(lo, hi); }
; __device__ __forceinline__ void hgrn_passC(LAS unsigned char* lds, const bf16_t* HQ, const bf16_t* HZ, const bf16_t* HVT, const bf16_t* HG, const float* LB, const bf16_t* ST,
;                                            const float* gnorm, bf16_t* Y, int b, int c, int h, int tid) {
;     ...
;     if (g == 0) SS[dvh * 64 + 16 * Iw + n] = ss;
;     __syncthreads();
;     const float tot = SS[16 * Iw + n] + SS[64 + 16 * Iw + n];
;     const float rstd = rsqrtf(tot * (1.0f / 128.0f) + RMS_EPS);
; #pragma unroll
;     for (int d4 = 0; d4 < 4; ++d4) {
;         const int dv = 16 * (4 * dvh + d4) + 4 * g;
;         const f32x4 gn = *(const f32x4*)(gnorm + dv);
;         const u32x2 hg = hgv[d4];
;         u32x2 ov; ov.x = pk2(o[d4][0] * rstd * gn[0] * bflo(hg.x), o[d4][1] * rstd * gn[1] * bfhi(hg.x)); ov.y = pk2(o[d4][2] * rstd * gn[2] * bflo(hg.y), o[d4][3] * rstd * gn[3] * bfhi(hg.y));
;         *(u32x2*)(Y + (tok0 + 16 * Iw + n) * DM + 1024 + h * 128 + dv) = ov;
;     }
.LBB0_347:
	s_or_b64 exec, exec, s[42:43]
	v_lshl_add_u64 v[20:21], v[64:65], 2, s[44:45]
	global_load_dwordx4 v[192:195], v[20:21], off
	global_load_dwordx4 v[196:199], v[20:21], off offset:64
	global_load_dwordx4 v[200:203], v[20:21], off offset:128
	global_load_dwordx4 v[204:207], v[20:21], off offset:192
	s_waitcnt lgkmcnt(0)
	s_barrier
	ds_read2st64_b32 v[22:23], v136 offset0:16 offset1:17
	v_lshlrev_b64 v[24:25], 12, v[72:73]
	v_lshl_add_u64 v[24:25], s[52:53], 0, v[24:25]
	v_lshl_add_u64 v[24:25], v[24:25], 0, s[72:73]
	s_waitcnt vmcnt(7)
	v_lshlrev_b32_e32 v26, 16, v74
	s_waitcnt lgkmcnt(0)
	v_add_f32_e32 v22, v22, v23
	v_fmamk_f32 v22, v22, 0x3c000000, v177
	v_mul_f32_e32 v23, 0x4b800000, v22
	v_cmp_gt_f32_e64 s[42:43], s83, v22
	v_and_b32_e32 v27, 0xffff0000, v74
	v_lshlrev_b32_e32 v28, 16, v75
	v_cndmask_b32_e64 v22, v22, v23, s[42:43]
	v_rsq_f32_e32 v30, v22
	v_and_b32_e32 v29, 0xffff0000, v75
	v_lshl_add_u64 v[24:25], v[64:65], 1, v[24:25]
	v_add_co_u32_e64 v22, s[44:45], s90, v24
	v_mul_f32_e32 v31, 0x45800000, v30
	v_cndmask_b32_e64 v30, v30, v31, s[42:43]
	v_pk_mul_f32 v[0:1], v[0:1], v[30:31] op_sel_hi:[1,0]
	v_pk_mul_f32 v[2:3], v[2:3], v[30:31] op_sel_hi:[1,0]
	v_addc_co_u32_e64 v23, s[44:45], 0, v25, s[44:45]
	v_pk_mul_f32 v[4:5], v[4:5], v[30:31] op_sel_hi:[1,0]
	v_pk_mul_f32 v[6:7], v[6:7], v[30:31] op_sel_hi:[1,0]
	v_pk_mul_f32 v[12:13], v[12:13], v[30:31] op_sel_hi:[1,0]
	v_pk_mul_f32 v[14:15], v[14:15], v[30:31] op_sel_hi:[1,0]
	v_pk_mul_f32 v[8:9], v[8:9], v[30:31] op_sel_hi:[1,0]
	v_pk_mul_f32 v[10:11], v[10:11], v[30:31] op_sel_hi:[1,0]
	s_add_i32 s91, s91, s54
	s_add_i32 s2, s2, s3
	v_lshl_add_u64 v[208:209], v[24:25], 0, s[74:75]
	s_waitcnt vmcnt(3)
	v_pk_mul_f32 v[0:1], v[192:193], v[0:1]
	v_pk_mul_f32 v[2:3], v[194:195], v[2:3]
	v_pk_mul_f32 v[0:1], v[0:1], v[26:27]
	v_pk_mul_f32 v[2:3], v[2:3], v[28:29]
	v_cvt_pk_bf16_f32 v0, v0, v1
	v_cvt_pk_bf16_f32 v1, v2, v3
	v_lshlrev_b32_e32 v16, 16, v70
	v_and_b32_e32 v17, 0xffff0000, v70
	v_lshlrev_b32_e32 v18, 16, v71
	v_and_b32_e32 v19, 0xffff0000, v71
	s_waitcnt vmcnt(2)
	v_pk_mul_f32 v[4:5], v[196:197], v[4:5]
	v_pk_mul_f32 v[6:7], v[198:199], v[6:7]
	v_pk_mul_f32 v[4:5], v[4:5], v[16:17]
	v_pk_mul_f32 v[6:7], v[6:7], v[18:19]
	v_cvt_pk_bf16_f32 v4, v4, v5
	v_cvt_pk_bf16_f32 v5, v6, v7
	v_lshlrev_b32_e32 v16, 16, v68
	v_and_b32_e32 v17, 0xffff0000, v68
	v_lshlrev_b32_e32 v18, 16, v69
	v_and_b32_e32 v19, 0xffff0000, v69
	s_waitcnt vmcnt(1)
	v_pk_mul_f32 v[12:13], v[200:201], v[12:13]
	v_pk_mul_f32 v[14:15], v[202:203], v[14:15]
	v_pk_mul_f32 v[12:13], v[12:13], v[16:17]
	v_pk_mul_f32 v[14:15], v[14:15], v[18:19]
	v_cvt_pk_bf16_f32 v12, v12, v13
	v_cvt_pk_bf16_f32 v13, v14, v15
	v_lshlrev_b32_e32 v16, 16, v66
	v_and_b32_e32 v17, 0xffff0000, v66
	v_lshlrev_b32_e32 v18, 16, v67
	v_and_b32_e32 v19, 0xffff0000, v67
	s_waitcnt vmcnt(0)
	v_pk_mul_f32 v[8:9], v[204:205], v[8:9]
	v_pk_mul_f32 v[10:11], v[206:207], v[10:11]
	v_pk_mul_f32 v[8:9], v[8:9], v[16:17]
	v_pk_mul_f32 v[10:11], v[10:11], v[18:19]
	v_cvt_pk_bf16_f32 v8, v8, v9
	v_cvt_pk_bf16_f32 v9, v10, v11
	global_store_dwordx2 v[22:23], v[0:1], off offset:2048
	global_store_dwordx2 v[208:209], v[4:5], off offset:32
	global_store_dwordx2 v[208:209], v[12:13], off offset:64
	global_store_dwordx2 v[208:209], v[8:9], off offset:96
	s_cmpk_gt_i32 s91, 0x7ff
	s_barrier
	s_cbranch_scc1 .LBB0_444
